# v33 plus: one extra early L2 write-back per XCD and barrier by the workgroup arriving 3rd from last (variant of the 6th-from-last version)
# baseline (speedup 1.0000x reference)
; __device__ __forceinline__ unsigned xb_ld(unsigned* p)              { return __hip_atomic_load(p, __ATOMIC_RELAXED, __HIP_MEMORY_SCOPE_AGENT); }
; __device__ __forceinline__ unsigned xb_add(unsigned* p, unsigned v) { return __hip_atomic_fetch_add(p, v, __ATOMIC_RELAXED, __HIP_MEMORY_SCOPE_AGENT); }
; #define XB_SPIN(cond, bar) do { unsigned _sp = 0; while (cond) { __builtin_amdgcn_s_sleep(1); \
;     if ((++_sp & 255u) == 0u) { if (xb_ld(&(bar)[XB_TMO])) break; if (_sp > XB_SPIN_CAP) { atomicAdd(&(bar)[XB_TMO], 1u); break; } } } } while (0)
; __device__ __forceinline__ void xcd_barrier(const XcdBarrier& b) {
;     ...
;         const unsigned old = xb_add(&bar[XB_XSUB(b.x)], 1u);
;         const unsigned gen = old / nloc;
;         if (old + 1u == (gen + 1u) * nloc) {
;             __builtin_amdgcn_fence(__ATOMIC_RELEASE, "agent");
;             asm volatile("s_waitcnt vmcnt(0)" ::: "memory");
;             const unsigned og = xb_add(&bar[XB_TOP], 1u);
;             const unsigned tg = og / nx;
;             if (og + 1u == (tg + 1u) * nx) xb_add(&bar[XB_TOPGEN], 1u);
;             else XB_SPIN(xb_ld(&bar[XB_TOPGEN]) == tg, bar);
;             __builtin_amdgcn_fence(__ATOMIC_ACQUIRE, "agent");
;             xb_add(&bar[XB_XGEN(b.x)], 1u);
;             asm volatile("s_waitcnt vmcnt(0)" ::: "memory");
;         } else {
;             XB_SPIN(xb_ld(&bar[XB_XGEN(b.x)]) == gen, bar);
.LBB0_117:
	s_or_b64 exec, exec, s[14:15]
	buffer_inv sc1
	v_cvt_f32_u32_e32 v4, v2
	s_waitcnt vmcnt(1)
	v_readfirstlane_b32 s12, v3
	v_sub_u32_e32 v3, 0, v2
	v_rcp_iflag_f32_e32 v4, v4
	v_add_u32_e32 v5, s12, v1
	v_mul_f32_e32 v4, 0x4f7ffffe, v4
	v_cvt_u32_f32_e32 v4, v4
	v_mul_lo_u32 v1, v3, v4
	v_mul_hi_u32 v1, v4, v1
	v_add_u32_e32 v1, v4, v1
	v_mul_hi_u32 v1, v5, v1
	v_mul_lo_u32 v3, v1, v2
	v_sub_u32_e32 v3, v5, v3
	v_add_u32_e32 v4, 1, v1
	v_cmp_ge_u32_e32 vcc, v3, v2
	s_nop 1
	v_cndmask_b32_e32 v1, v1, v4, vcc
	v_sub_u32_e32 v4, v3, v2
	v_cndmask_b32_e32 v3, v3, v4, vcc
	v_add_u32_e32 v4, 1, v1
	v_cmp_ge_u32_e32 vcc, v3, v2
	v_add_u32_e32 v3, 1, v5
	s_nop 0
	v_cndmask_b32_e32 v1, v1, v4, vcc
	v_mul_lo_u32 v4, v2, v1
	v_add_u32_e32 v2, v4, v2
	v_cmp_ne_u32_e32 vcc, v3, v2
	s_and_saveexec_b64 s[12:13], vcc
	s_xor_b64 s[12:13], exec, s[12:13]
	s_cbranch_execz .LBB0_131
	v_sub_u32_e32 v251, v2, v3
	v_cmp_eq_u32_e32 vcc, 3, v251
	s_cbranch_vccz .Lbar_noearly_0
	buffer_wbl2 sc1

; __device__ __forceinline__ unsigned xb_ld(unsigned* p)              { return __hip_atomic_load(p, __ATOMIC_RELAXED, __HIP_MEMORY_SCOPE_AGENT); }
; __device__ __forceinline__ unsigned xb_add(unsigned* p, unsigned v) { return __hip_atomic_fetch_add(p, v, __ATOMIC_RELAXED, __HIP_MEMORY_SCOPE_AGENT); }
; #define XB_SPIN(cond, bar) do { unsigned _sp = 0; while (cond) { __builtin_amdgcn_s_sleep(1); \
;     if ((++_sp & 255u) == 0u) { if (xb_ld(&(bar)[XB_TMO])) break; if (_sp > XB_SPIN_CAP) { atomicAdd(&(bar)[XB_TMO], 1u); break; } } } } while (0)
; __device__ __forceinline__ void xcd_barrier(const XcdBarrier& b) {
;     ...
;         const unsigned old = xb_add(&bar[XB_XSUB(b.x)], 1u);
;         const unsigned gen = old / nloc;
;         if (old + 1u == (gen + 1u) * nloc) {
;             __builtin_amdgcn_fence(__ATOMIC_RELEASE, "agent");
;             asm volatile("s_waitcnt vmcnt(0)" ::: "memory");
;             const unsigned og = xb_add(&bar[XB_TOP], 1u);
;             const unsigned tg = og / nx;
;             if (og + 1u == (tg + 1u) * nx) xb_add(&bar[XB_TOPGEN], 1u);
;             else XB_SPIN(xb_ld(&bar[XB_TOPGEN]) == tg, bar);
;             __builtin_amdgcn_fence(__ATOMIC_ACQUIRE, "agent");
;             xb_add(&bar[XB_XGEN(b.x)], 1u);
;             asm volatile("s_waitcnt vmcnt(0)" ::: "memory");
;         } else {
;             XB_SPIN(xb_ld(&bar[XB_XGEN(b.x)]) == gen, bar);
.LBB0_328:
	s_or_b64 exec, exec, s[12:13]
	buffer_inv sc1
	v_cvt_f32_u32_e32 v4, v2
	s_waitcnt vmcnt(1)
	v_readfirstlane_b32 s10, v3
	v_sub_u32_e32 v3, 0, v2
	v_rcp_iflag_f32_e32 v4, v4
	v_add_u32_e32 v5, s10, v1
	v_mul_f32_e32 v4, 0x4f7ffffe, v4
	v_cvt_u32_f32_e32 v4, v4
	v_mul_lo_u32 v1, v3, v4
	v_mul_hi_u32 v1, v4, v1
	v_add_u32_e32 v1, v4, v1
	v_mul_hi_u32 v1, v5, v1
	v_mul_lo_u32 v3, v1, v2
	v_sub_u32_e32 v3, v5, v3
	v_add_u32_e32 v4, 1, v1
	v_cmp_ge_u32_e32 vcc, v3, v2
	s_nop 1
	v_cndmask_b32_e32 v1, v1, v4, vcc
	v_sub_u32_e32 v4, v3, v2
	v_cndmask_b32_e32 v3, v3, v4, vcc
	v_add_u32_e32 v4, 1, v1
	v_cmp_ge_u32_e32 vcc, v3, v2
	v_add_u32_e32 v3, 1, v5
	s_nop 0
	v_cndmask_b32_e32 v1, v1, v4, vcc
	v_mul_lo_u32 v4, v2, v1
	v_add_u32_e32 v2, v4, v2
	v_cmp_ne_u32_e32 vcc, v3, v2
	s_and_saveexec_b64 s[10:11], vcc
	s_xor_b64 s[10:11], exec, s[10:11]
	s_cbranch_execz .LBB0_342
	v_sub_u32_e32 v251, v2, v3
	v_cmp_eq_u32_e32 vcc, 3, v251
	s_cbranch_vccz .Lbar_noearly_1
	buffer_wbl2 sc1

; __device__ __forceinline__ unsigned xb_ld(unsigned* p)              { return __hip_atomic_load(p, __ATOMIC_RELAXED, __HIP_MEMORY_SCOPE_AGENT); }
; __device__ __forceinline__ unsigned xb_add(unsigned* p, unsigned v) { return __hip_atomic_fetch_add(p, v, __ATOMIC_RELAXED, __HIP_MEMORY_SCOPE_AGENT); }
; #define XB_SPIN(cond, bar) do { unsigned _sp = 0; while (cond) { __builtin_amdgcn_s_sleep(1); \
;     if ((++_sp & 255u) == 0u) { if (xb_ld(&(bar)[XB_TMO])) break; if (_sp > XB_SPIN_CAP) { atomicAdd(&(bar)[XB_TMO], 1u); break; } } } } while (0)
; __device__ __forceinline__ void xcd_barrier(const XcdBarrier& b) {
;     ...
;         const unsigned old = xb_add(&bar[XB_XSUB(b.x)], 1u);
;         const unsigned gen = old / nloc;
;         if (old + 1u == (gen + 1u) * nloc) {
;             __builtin_amdgcn_fence(__ATOMIC_RELEASE, "agent");
;             asm volatile("s_waitcnt vmcnt(0)" ::: "memory");
;             const unsigned og = xb_add(&bar[XB_TOP], 1u);
;             const unsigned tg = og / nx;
;             if (og + 1u == (tg + 1u) * nx) xb_add(&bar[XB_TOPGEN], 1u);
;             else XB_SPIN(xb_ld(&bar[XB_TOPGEN]) == tg, bar);
;             __builtin_amdgcn_fence(__ATOMIC_ACQUIRE, "agent");
;             xb_add(&bar[XB_XGEN(b.x)], 1u);
;             asm volatile("s_waitcnt vmcnt(0)" ::: "memory");
;         } else {
;             XB_SPIN(xb_ld(&bar[XB_XGEN(b.x)]) == gen, bar);
.LBB0_419:
	s_or_b64 exec, exec, s[22:23]
	buffer_inv sc1
	v_cvt_f32_u32_e32 v4, v2
	s_waitcnt vmcnt(1)
	v_readfirstlane_b32 s11, v3
	v_sub_u32_e32 v3, 0, v2
	v_rcp_iflag_f32_e32 v4, v4
	v_add_u32_e32 v5, s11, v1
	v_mul_f32_e32 v4, 0x4f7ffffe, v4
	v_cvt_u32_f32_e32 v4, v4
	v_mul_lo_u32 v1, v3, v4
	v_mul_hi_u32 v1, v4, v1
	v_add_u32_e32 v1, v4, v1
	v_mul_hi_u32 v1, v5, v1
	v_mul_lo_u32 v3, v1, v2
	v_sub_u32_e32 v3, v5, v3
	v_add_u32_e32 v4, 1, v1
	v_cmp_ge_u32_e32 vcc, v3, v2
	s_nop 1
	v_cndmask_b32_e32 v1, v1, v4, vcc
	v_sub_u32_e32 v4, v3, v2
	v_cndmask_b32_e32 v3, v3, v4, vcc
	v_add_u32_e32 v4, 1, v1
	v_cmp_ge_u32_e32 vcc, v3, v2
	v_add_u32_e32 v3, 1, v5
	s_nop 0
	v_cndmask_b32_e32 v1, v1, v4, vcc
	v_mul_lo_u32 v4, v2, v1
	v_add_u32_e32 v2, v4, v2
	v_cmp_ne_u32_e32 vcc, v3, v2
	s_and_saveexec_b64 s[12:13], vcc
	s_xor_b64 s[22:23], exec, s[12:13]
	s_cbranch_execz .LBB0_433
	v_sub_u32_e32 v251, v2, v3
	v_cmp_eq_u32_e32 vcc, 3, v251
	s_cbranch_vccz .Lbar_noearly_2
	buffer_wbl2 sc1

; __device__ __forceinline__ unsigned xb_ld(unsigned* p)              { return __hip_atomic_load(p, __ATOMIC_RELAXED, __HIP_MEMORY_SCOPE_AGENT); }
; __device__ __forceinline__ unsigned xb_add(unsigned* p, unsigned v) { return __hip_atomic_fetch_add(p, v, __ATOMIC_RELAXED, __HIP_MEMORY_SCOPE_AGENT); }
; #define XB_SPIN(cond, bar) do { unsigned _sp = 0; while (cond) { __builtin_amdgcn_s_sleep(1); \
;     if ((++_sp & 255u) == 0u) { if (xb_ld(&(bar)[XB_TMO])) break; if (_sp > XB_SPIN_CAP) { atomicAdd(&(bar)[XB_TMO], 1u); break; } } } } while (0)
; __device__ __forceinline__ void xcd_barrier(const XcdBarrier& b) {
;     ...
;         const unsigned old = xb_add(&bar[XB_XSUB(b.x)], 1u);
;         const unsigned gen = old / nloc;
;         if (old + 1u == (gen + 1u) * nloc) {
;             __builtin_amdgcn_fence(__ATOMIC_RELEASE, "agent");
;             asm volatile("s_waitcnt vmcnt(0)" ::: "memory");
;             const unsigned og = xb_add(&bar[XB_TOP], 1u);
;             const unsigned tg = og / nx;
;             if (og + 1u == (tg + 1u) * nx) xb_add(&bar[XB_TOPGEN], 1u);
;             else XB_SPIN(xb_ld(&bar[XB_TOPGEN]) == tg, bar);
;             __builtin_amdgcn_fence(__ATOMIC_ACQUIRE, "agent");
;             xb_add(&bar[XB_XGEN(b.x)], 1u);
;             asm volatile("s_waitcnt vmcnt(0)" ::: "memory");
;         } else {
;             XB_SPIN(xb_ld(&bar[XB_XGEN(b.x)]) == gen, bar);
.LBB0_1389:
	s_or_b64 exec, exec, s[22:23]
	buffer_inv sc1
	v_cvt_f32_u32_e32 v4, v2
	s_waitcnt vmcnt(1)
	v_readfirstlane_b32 s6, v3
	v_sub_u32_e32 v3, 0, v2
	v_rcp_iflag_f32_e32 v4, v4
	v_add_u32_e32 v5, s6, v1
	v_mul_f32_e32 v4, 0x4f7ffffe, v4
	v_cvt_u32_f32_e32 v4, v4
	v_mul_lo_u32 v1, v3, v4
	v_mul_hi_u32 v1, v4, v1
	v_add_u32_e32 v1, v4, v1
	v_mul_hi_u32 v1, v5, v1
	v_mul_lo_u32 v3, v1, v2
	v_sub_u32_e32 v3, v5, v3
	v_add_u32_e32 v4, 1, v1
	v_cmp_ge_u32_e32 vcc, v3, v2
	s_nop 1
	v_cndmask_b32_e32 v1, v1, v4, vcc
	v_sub_u32_e32 v4, v3, v2
	v_cndmask_b32_e32 v3, v3, v4, vcc
	v_add_u32_e32 v4, 1, v1
	v_cmp_ge_u32_e32 vcc, v3, v2
	v_add_u32_e32 v3, 1, v5
	s_nop 0
	v_cndmask_b32_e32 v1, v1, v4, vcc
	v_mul_lo_u32 v4, v2, v1
	v_add_u32_e32 v2, v4, v2
	v_cmp_ne_u32_e32 vcc, v3, v2
	s_and_saveexec_b64 s[16:17], vcc
	s_xor_b64 s[22:23], exec, s[16:17]
	s_cbranch_execz .LBB0_1403
	v_sub_u32_e32 v251, v2, v3
	v_cmp_eq_u32_e32 vcc, 3, v251
	s_cbranch_vccz .Lbar_noearly_8
	buffer_wbl2 sc1

; __device__ __forceinline__ unsigned xb_ld(unsigned* p)              { return __hip_atomic_load(p, __ATOMIC_RELAXED, __HIP_MEMORY_SCOPE_AGENT); }
; __device__ __forceinline__ unsigned xb_add(unsigned* p, unsigned v) { return __hip_atomic_fetch_add(p, v, __ATOMIC_RELAXED, __HIP_MEMORY_SCOPE_AGENT); }
; #define XB_SPIN(cond, bar) do { unsigned _sp = 0; while (cond) { __builtin_amdgcn_s_sleep(1); \
;     if ((++_sp & 255u) == 0u) { if (xb_ld(&(bar)[XB_TMO])) break; if (_sp > XB_SPIN_CAP) { atomicAdd(&(bar)[XB_TMO], 1u); break; } } } } while (0)
; __device__ __forceinline__ void xcd_barrier(const XcdBarrier& b) {
;     ...
;         const unsigned old = xb_add(&bar[XB_XSUB(b.x)], 1u);
;         const unsigned gen = old / nloc;
;         if (old + 1u == (gen + 1u) * nloc) {
;             __builtin_amdgcn_fence(__ATOMIC_RELEASE, "agent");
;             asm volatile("s_waitcnt vmcnt(0)" ::: "memory");
;             const unsigned og = xb_add(&bar[XB_TOP], 1u);
;             const unsigned tg = og / nx;
;             if (og + 1u == (tg + 1u) * nx) xb_add(&bar[XB_TOPGEN], 1u);
;             else XB_SPIN(xb_ld(&bar[XB_TOPGEN]) == tg, bar);
;             __builtin_amdgcn_fence(__ATOMIC_ACQUIRE, "agent");
;             xb_add(&bar[XB_XGEN(b.x)], 1u);
;             asm volatile("s_waitcnt vmcnt(0)" ::: "memory");
;         } else {
;             XB_SPIN(xb_ld(&bar[XB_XGEN(b.x)]) == gen, bar);
.LBB0_2162:
	s_or_b64 exec, exec, s[22:23]
	buffer_inv sc1
	v_cvt_f32_u32_e32 v4, v2
	s_waitcnt vmcnt(1)
	v_readfirstlane_b32 s6, v3
	v_sub_u32_e32 v3, 0, v2
	v_rcp_iflag_f32_e32 v4, v4
	v_add_u32_e32 v5, s6, v1
	v_mul_f32_e32 v4, 0x4f7ffffe, v4
	v_cvt_u32_f32_e32 v4, v4
	v_mul_lo_u32 v1, v3, v4
	v_mul_hi_u32 v1, v4, v1
	v_add_u32_e32 v1, v4, v1
	v_mul_hi_u32 v1, v5, v1
	v_mul_lo_u32 v3, v1, v2
	v_sub_u32_e32 v3, v5, v3
	v_add_u32_e32 v4, 1, v1
	v_cmp_ge_u32_e32 vcc, v3, v2
	s_nop 1
	v_cndmask_b32_e32 v1, v1, v4, vcc
	v_sub_u32_e32 v4, v3, v2
	v_cndmask_b32_e32 v3, v3, v4, vcc
	v_add_u32_e32 v4, 1, v1
	v_cmp_ge_u32_e32 vcc, v3, v2
	v_add_u32_e32 v3, 1, v5
	s_nop 0
	v_cndmask_b32_e32 v1, v1, v4, vcc
	v_mul_lo_u32 v4, v2, v1
	v_add_u32_e32 v2, v4, v2
	v_cmp_ne_u32_e32 vcc, v3, v2
	s_and_saveexec_b64 s[14:15], vcc
	s_xor_b64 s[22:23], exec, s[14:15]
	s_cbranch_execz .LBB0_2176
	v_sub_u32_e32 v251, v2, v3
	v_cmp_eq_u32_e32 vcc, 3, v251
	s_cbranch_vccz .Lbar_noearly_14
	buffer_wbl2 sc1

; __device__ __forceinline__ unsigned xb_ld(unsigned* p)              { return __hip_atomic_load(p, __ATOMIC_RELAXED, __HIP_MEMORY_SCOPE_AGENT); }
; __device__ __forceinline__ unsigned xb_add(unsigned* p, unsigned v) { return __hip_atomic_fetch_add(p, v, __ATOMIC_RELAXED, __HIP_MEMORY_SCOPE_AGENT); }
; #define XB_SPIN(cond, bar) do { unsigned _sp = 0; while (cond) { __builtin_amdgcn_s_sleep(1); \
;     if ((++_sp & 255u) == 0u) { if (xb_ld(&(bar)[XB_TMO])) break; if (_sp > XB_SPIN_CAP) { atomicAdd(&(bar)[XB_TMO], 1u); break; } } } } while (0)
; __device__ __forceinline__ void xcd_barrier(const XcdBarrier& b) {
;     ...
;         const unsigned old = xb_add(&bar[XB_XSUB(b.x)], 1u);
;         const unsigned gen = old / nloc;
;         if (old + 1u == (gen + 1u) * nloc) {
;             __builtin_amdgcn_fence(__ATOMIC_RELEASE, "agent");
;             asm volatile("s_waitcnt vmcnt(0)" ::: "memory");
;             const unsigned og = xb_add(&bar[XB_TOP], 1u);
;             const unsigned tg = og / nx;
;             if (og + 1u == (tg + 1u) * nx) xb_add(&bar[XB_TOPGEN], 1u);
;             else XB_SPIN(xb_ld(&bar[XB_TOPGEN]) == tg, bar);
;             __builtin_amdgcn_fence(__ATOMIC_ACQUIRE, "agent");
;             xb_add(&bar[XB_XGEN(b.x)], 1u);
;             asm volatile("s_waitcnt vmcnt(0)" ::: "memory");
;         } else {
;             XB_SPIN(xb_ld(&bar[XB_XGEN(b.x)]) == gen, bar);
.LBB0_2258:
	s_or_b64 exec, exec, s[22:23]
	buffer_inv sc1
	v_cvt_f32_u32_e32 v4, v2
	s_waitcnt vmcnt(1)
	v_readfirstlane_b32 s11, v3
	v_sub_u32_e32 v3, 0, v2
	v_rcp_iflag_f32_e32 v4, v4
	v_add_u32_e32 v5, s11, v1
	v_mul_f32_e32 v4, 0x4f7ffffe, v4
	v_cvt_u32_f32_e32 v4, v4
	v_mul_lo_u32 v1, v3, v4
	v_mul_hi_u32 v1, v4, v1
	v_add_u32_e32 v1, v4, v1
	v_mul_hi_u32 v1, v5, v1
	v_mul_lo_u32 v3, v1, v2
	v_sub_u32_e32 v3, v5, v3
	v_add_u32_e32 v4, 1, v1
	v_cmp_ge_u32_e32 vcc, v3, v2
	s_nop 1
	v_cndmask_b32_e32 v1, v1, v4, vcc
	v_sub_u32_e32 v4, v3, v2
	v_cndmask_b32_e32 v3, v3, v4, vcc
	v_add_u32_e32 v4, 1, v1
	v_cmp_ge_u32_e32 vcc, v3, v2
	v_add_u32_e32 v3, 1, v5
	s_nop 0
	v_cndmask_b32_e32 v1, v1, v4, vcc
	v_mul_lo_u32 v4, v2, v1
	v_add_u32_e32 v2, v4, v2
	v_cmp_ne_u32_e32 vcc, v3, v2
	s_and_saveexec_b64 s[14:15], vcc
	s_xor_b64 s[22:23], exec, s[14:15]
	s_cbranch_execz .LBB0_2272
	v_sub_u32_e32 v251, v2, v3
	v_cmp_eq_u32_e32 vcc, 3, v251
	s_cbranch_vccz .Lbar_noearly_15
	buffer_wbl2 sc1

; __device__ __forceinline__ unsigned xb_ld(unsigned* p)              { return __hip_atomic_load(p, __ATOMIC_RELAXED, __HIP_MEMORY_SCOPE_AGENT); }
; __device__ __forceinline__ unsigned xb_add(unsigned* p, unsigned v) { return __hip_atomic_fetch_add(p, v, __ATOMIC_RELAXED, __HIP_MEMORY_SCOPE_AGENT); }
; #define XB_SPIN(cond, bar) do { unsigned _sp = 0; while (cond) { __builtin_amdgcn_s_sleep(1); \
;     if ((++_sp & 255u) == 0u) { if (xb_ld(&(bar)[XB_TMO])) break; if (_sp > XB_SPIN_CAP) { atomicAdd(&(bar)[XB_TMO], 1u); break; } } } } while (0)
; __device__ __forceinline__ void xcd_barrier(const XcdBarrier& b) {
;     ...
;         const unsigned old = xb_add(&bar[XB_XSUB(b.x)], 1u);
;         const unsigned gen = old / nloc;
;         if (old + 1u == (gen + 1u) * nloc) {
;             __builtin_amdgcn_fence(__ATOMIC_RELEASE, "agent");
;             asm volatile("s_waitcnt vmcnt(0)" ::: "memory");
;             const unsigned og = xb_add(&bar[XB_TOP], 1u);
;             const unsigned tg = og / nx;
;             if (og + 1u == (tg + 1u) * nx) xb_add(&bar[XB_TOPGEN], 1u);
;             else XB_SPIN(xb_ld(&bar[XB_TOPGEN]) == tg, bar);
;             __builtin_amdgcn_fence(__ATOMIC_ACQUIRE, "agent");
;             xb_add(&bar[XB_XGEN(b.x)], 1u);
;             asm volatile("s_waitcnt vmcnt(0)" ::: "memory");
;         } else {
;             XB_SPIN(xb_ld(&bar[XB_XGEN(b.x)]) == gen, bar);
.LBB0_2618:
	s_or_b64 exec, exec, s[2:3]
	buffer_inv sc1
	v_cvt_f32_u32_e32 v4, v2
	s_waitcnt vmcnt(1)
	v_readfirstlane_b32 s2, v3
	v_sub_u32_e32 v3, 0, v2
	v_rcp_iflag_f32_e32 v4, v4
	v_add_u32_e32 v5, s2, v1
	v_mul_f32_e32 v4, 0x4f7ffffe, v4
	v_cvt_u32_f32_e32 v4, v4
	v_mul_lo_u32 v1, v3, v4
	v_mul_hi_u32 v1, v4, v1
	v_add_u32_e32 v1, v4, v1
	v_mul_hi_u32 v1, v5, v1
	v_mul_lo_u32 v3, v1, v2
	v_sub_u32_e32 v3, v5, v3
	v_add_u32_e32 v4, 1, v1
	v_cmp_ge_u32_e32 vcc, v3, v2
	s_nop 1
	v_cndmask_b32_e32 v1, v1, v4, vcc
	v_sub_u32_e32 v4, v3, v2
	v_cndmask_b32_e32 v3, v3, v4, vcc
	v_add_u32_e32 v4, 1, v1
	v_cmp_ge_u32_e32 vcc, v3, v2
	v_add_u32_e32 v3, 1, v5
	s_nop 0
	v_cndmask_b32_e32 v1, v1, v4, vcc
	v_mul_lo_u32 v4, v2, v1
	v_add_u32_e32 v2, v4, v2
	v_cmp_ne_u32_e32 vcc, v3, v2
	s_and_saveexec_b64 s[2:3], vcc
	s_xor_b64 s[2:3], exec, s[2:3]
	s_cbranch_execz .LBB0_2632
	v_sub_u32_e32 v251, v2, v3
	v_cmp_eq_u32_e32 vcc, 3, v251
	s_cbranch_vccz .Lbar_noearly_17
	buffer_wbl2 sc1
